# GEMM tile queue: the next-tile pop atomic returns into its holding register and is waited at the loop top instead of right after issue
# speedup vs baseline: 1.0042x; 1.0042x over previous
.LBB0_109:
	s_or_b64 exec, exec, s[0:1]
	v_readlane_b32 s0, v253, 27
	s_waitcnt lgkmcnt(0)
	s_barrier
	v_mov_b32_e32 v0, s0
	ds_read_b32 v0, v0
	v_readlane_b32 s0, v254, 22
	s_waitcnt lgkmcnt(0)
	v_readfirstlane_b32 s3, v0
	s_cmp_ge_i32 s3, s0
	s_cselect_b64 s[64:65], -1, 0
	s_and_b64 vcc, exec, s[64:65]
	s_cbranch_vccnz .LBB0_106
	s_mov_b64 s[0:1], exec
	v_readlane_b32 s4, v255, 27
	v_readlane_b32 s5, v255, 28
	s_and_b64 s[4:5], s[0:1], s[4:5]
	s_mov_b64 exec, s[4:5]
	s_cbranch_execz .LBB0_114
	s_mov_b64 s[6:7], exec
	v_mbcnt_lo_u32_b32 v0, s6, 0
	v_mbcnt_hi_u32_b32 v0, s7, v0
	v_cmp_eq_u32_e32 vcc, 0, v0
	s_and_saveexec_b64 s[4:5], vcc
	s_cbranch_execz .LBB0_113
	s_bcnt1_i32_b64 s2, s[6:7]
	v_readlane_b32 s6, v255, 25
	v_mov_b32_e32 v1, s2
	v_readlane_b32 s7, v255, 26
	s_nop 4
	global_atomic_add v164, v9, v1, s[6:7] sc0
.LBB0_113:
	s_or_b64 exec, exec, s[4:5]
.LBB0_114:
	s_or_b64 exec, exec, s[0:1]
	s_abs_i32 s1, s3
	v_readlane_b32 s2, v255, 10
	s_mul_hi_u32 s2, s1, s2
	v_readlane_b32 s6, v255, 9
	s_mul_i32 s4, s2, s6
	s_sub_i32 s1, s1, s4
	s_ashr_i32 s0, s3, 31
	s_add_i32 s4, s2, 1
	s_sub_i32 s5, s1, s6
	s_cmp_ge_u32 s1, s6
	s_cselect_b32 s2, s4, s2
	s_cselect_b32 s1, s5, s1
	s_add_i32 s4, s2, 1
	s_cmp_ge_u32 s1, s6
	s_cselect_b32 s1, s4, s2
	s_xor_b32 s1, s1, s0
	s_sub_i32 s2, s1, s0
	s_mul_i32 s0, s2, s6
	s_sub_i32 s3, s3, s0
	v_readlane_b32 s0, v254, 21
	s_add_i32 s3, s3, s0
	v_mov_b32_e32 v1, v203
	s_cmp_gt_i32 s3, 1
	v_readfirstlane_b32 s6, v1
	s_mov_b64 s[0:1], -1
	s_cbranch_scc0 .LBB0_116
	s_lshl_b32 s0, s2, 12
	s_lshl_b32 s1, s3, 7
	s_add_i32 s0, s0, s1
	s_add_i32 s24, s0, 0xffffff00
	s_mov_b64 s[0:1], 0
